# seam-10 R4 quarter: no store drain before the barrier poll (stores complete under ff2b)
# speedup vs baseline: 1.0004x; 1.0004x over previous
.Llb865_arrdone:
	s_mov_b64 exec, s[8:9]
	v_writelane_b32 v255, s0, 40
	v_writelane_b32 v255, s1, 41
	v_writelane_b32 v255, s2, 42
	v_writelane_b32 v255, s3, 43
	v_writelane_b32 v255, s6, 44
	v_writelane_b32 v255, s7, 45
	v_writelane_b32 v255, s25, 46
	v_writelane_b32 v255, s26, 47
	v_writelane_b32 v255, s27, 48
	v_writelane_b32 v255, s28, 49
	v_writelane_b32 v255, s49, 50
	v_mov_b32_e32 v222, v1
	v_mov_b32_e32 v223, v138
	v_mov_b32_e32 v224, v139
	v_mov_b32_e32 v225, v140
	v_mov_b32_e32 v226, v141
	v_mov_b32_e32 v227, v142
	v_mov_b32_e32 v228, v143
	v_mov_b32_e32 v229, v144
	v_mov_b32_e32 v230, v145
	v_mov_b32_e32 v231, v154
	v_mov_b32_e32 v232, v155
	v_mov_b32_e32 v233, v156
	v_mov_b32_e32 v234, v157
	v_mov_b32_e32 v235, v158
	v_mov_b32_e32 v236, v159
	v_mov_b32_e32 v237, v160
	s_movk_i32 s9, 0x2000
	v_mbcnt_lo_u32_b32 v1, -1, 0
	v_mbcnt_hi_u32_b32 v3, -1, v1
	v_and_b32_e32 v1, 64, v3
	v_add_u32_e32 v4, 64, v1
	v_xor_b32_e32 v1, 1, v3
	v_cmp_lt_i32_e32 vcc, v1, v4
	v_xor_b32_e32 v6, 2, v3
	s_lshl_b32 s2, s44, 1
	v_cndmask_b32_e32 v1, v3, v1, vcc
	v_cmp_lt_i32_e32 vcc, v6, v4
	v_lshlrev_b32_e32 v2, 3, v191
	v_mov_b32_e32 v5, 0
	v_cndmask_b32_e32 v6, v3, v6, vcc
	v_lshlrev_b32_e32 v61, 2, v6
	v_xor_b32_e32 v6, 4, v3
	v_cmp_lt_i32_e32 vcc, v6, v4
	v_or_b32_e32 v8, 0x400, v2
	s_ashr_i32 s3, s2, 31
	v_cndmask_b32_e32 v6, v3, v6, vcc
	v_lshlrev_b32_e32 v75, 2, v6
	v_xor_b32_e32 v6, 8, v3
	v_cmp_lt_i32_e32 vcc, v6, v4
	v_or_b32_e32 v10, 0x600, v2
	v_lshlrev_b32_e32 v12, 2, v8
	v_cndmask_b32_e32 v6, v3, v6, vcc
	v_mov_b32_e32 v13, v5
	s_lshl_b64 s[0:1], s[2:3], 12
	v_lshlrev_b32_e32 v77, 2, v6
	v_xor_b32_e32 v6, 16, v3
	v_lshl_add_u64 v[52:53], s[58:59], 0, v[12:13]
	v_lshlrev_b32_e32 v12, 2, v10
	s_add_u32 s0, s62, s0
	v_cmp_lt_i32_e32 vcc, v6, v4
	v_lshl_add_u64 v[54:55], s[58:59], 0, v[12:13]
	v_lshlrev_b32_e32 v12, 4, v191
	s_addc_u32 s1, s63, s1
	v_cndmask_b32_e32 v6, v3, v6, vcc
	v_lshl_add_u64 v[12:13], s[0:1], 0, v[12:13]
	s_mov_b64 s[0:1], 0x10800000
	s_ashr_i32 s49, s48, 31
	v_lshlrev_b32_e32 v94, 2, v6
	v_xor_b32_e32 v6, 32, v3
	v_lshl_add_u64 v[56:57], v[12:13], 0, s[0:1]
	s_lshl_b64 s[4:5], s[48:49], 12
	s_lshl_b64 s[0:1], s[2:3], 13
	v_cmp_lt_i32_e32 vcc, v6, v4
	s_add_u32 s0, s60, s0
	v_lshlrev_b32_e32 v4, 5, v191
	v_cndmask_b32_e32 v3, v3, v6, vcc
	v_or_b32_e32 v6, 0x200, v2
	s_addc_u32 s1, s61, s1
	v_lshlrev_b32_e32 v1, 2, v1
	v_lshlrev_b32_e32 v95, 2, v3
	v_lshl_add_u64 v[50:51], s[58:59], 0, v[4:5]
	v_lshl_add_u64 v[58:59], s[0:1], 0, v[4:5]
	s_lshl_b64 s[6:7], s[48:49], 13
	s_movk_i32 s3, 0x1000
	s_mov_b32 s12, 0x4001000
	v_lshlrev_b32_e32 v96, 2, v2
	v_lshlrev_b32_e32 v97, 2, v6
	v_lshlrev_b32_e32 v98, 2, v8
	v_lshlrev_b32_e32 v99, 2, v10
	s_mov_b32 s8, 0x3a000000
	s_mov_b32 s13, 0x800000
	s_movk_i32 s14, 0x3000
	v_mov_b32_e32 v60, 0x358637bd
	v_add_co_u32_e32 v30, vcc, 0x4000000, v56
	global_load_dwordx4 v[22:25], v[56:57], off
	global_load_dwordx4 v[18:21], v[56:57], off offset:1024
	global_load_dwordx4 v[14:17], v[56:57], off offset:2048
	global_load_dwordx4 v[10:13], v[56:57], off offset:3072
	v_addc_co_u32_e32 v31, vcc, 0, v57, vcc
	v_add_co_u32_e32 v32, vcc, s3, v56
	global_load_dwordx4 v[2:5], v[50:51], off offset:16
	global_load_dwordx4 v[6:9], v[50:51], off
	v_addc_co_u32_e32 v33, vcc, 0, v57, vcc
	global_load_dwordx4 v[78:81], v[30:31], off
	global_load_dwordx4 v[42:45], v[30:31], off offset:1024
	global_load_dwordx4 v[34:37], v[30:31], off offset:2048
	global_load_dwordx4 v[26:29], v[30:31], off offset:3072
	global_load_dwordx4 v[82:85], v[32:33], off
	global_load_dwordx4 v[100:103], v[32:33], off offset:1024
	global_load_dwordx4 v[104:107], v[32:33], off offset:2048
	global_load_dwordx4 v[108:111], v[32:33], off offset:3072
	v_add_co_u32_e32 v66, vcc, s12, v56
	v_add_co_u32_e64 v64, s[0:1], s9, v58
	s_nop 0
	v_addc_co_u32_e32 v67, vcc, 0, v57, vcc
	global_load_dwordx4 v[112:115], v[66:67], off
	global_load_dwordx4 v[46:49], v[66:67], off offset:1024
	global_load_dwordx4 v[38:41], v[66:67], off offset:2048
	global_load_dwordx4 v[30:33], v[66:67], off offset:3072
	v_addc_co_u32_e64 v65, s[0:1], 0, v59, s[0:1]
	v_add_co_u32_e64 v62, s[0:1], s14, v58
	s_add_i32 s10, s2, 0xffffe000
	s_nop 0
	v_addc_co_u32_e64 v63, s[0:1], 0, v59, s[0:1]
	s_lshr_b32 s0, s10, 10
	s_add_i32 s0, s0, 1
	s_cmpk_gt_i32 s2, 0x1fff
	s_cselect_b32 s0, s0, 0
	s_mul_hi_u32 s1, s0, 0xc000
	s_mul_i32 s0, s0, 0xc000
	s_add_u32 s0, s62, s0
	s_addc_u32 s1, s63, s1
	s_add_u32 s10, s0, 0xa000
	s_addc_u32 s11, s1, 0
	global_load_dwordx4 v[116:119], v96, s[10:11] offset:16
	global_load_dwordx4 v[120:123], v96, s[10:11]
	s_add_i32 s2, s2, s48
	v_lshl_add_u64 v[56:57], v[56:57], 0, s[4:5]
	s_cmpk_lt_i32 s2, 0x4000
	s_waitcnt vmcnt(0)
	v_and_b32_e32 v125, 0xffff0000, v22
	v_lshlrev_b32_e32 v124, 16, v22
	v_lshlrev_b32_e32 v126, 16, v23
	v_and_b32_e32 v127, 0xffff0000, v23
	v_lshlrev_b32_e32 v70, 16, v16
	v_and_b32_e32 v71, 0xffff0000, v16
	v_lshlrev_b32_e32 v72, 16, v17
	v_and_b32_e32 v73, 0xffff0000, v17
	v_lshlrev_b32_e32 v16, 16, v12
	v_and_b32_e32 v207, 0xffff0000, v82
	v_and_b32_e32 v17, 0xffff0000, v12
	v_mov_b32_e32 v137, v125
	v_lshlrev_b32_e32 v206, 16, v82
	v_lshlrev_b32_e32 v22, 16, v110
	v_and_b32_e32 v23, 0xffff0000, v110
	v_mov_b32_e32 v136, v207
	v_lshlrev_b32_e32 v86, 16, v18
	v_and_b32_e32 v87, 0xffff0000, v18
	v_lshlrev_b32_e32 v88, 16, v19
	v_and_b32_e32 v89, 0xffff0000, v19
	v_lshlrev_b32_e32 v90, 16, v20
	v_and_b32_e32 v91, 0xffff0000, v20
	v_lshlrev_b32_e32 v92, 16, v21
	v_and_b32_e32 v93, 0xffff0000, v21
	v_mov_b32_e32 v135, v124
	v_pk_mul_f32 v[170:171], v[16:17], v[16:17]
	v_lshlrev_b32_e32 v208, 16, v83
	v_lshlrev_b32_e32 v214, 16, v100
	v_and_b32_e32 v215, 0xffff0000, v100
	v_lshlrev_b32_e32 v216, 16, v101
	v_and_b32_e32 v217, 0xffff0000, v101
	v_lshlrev_b32_e32 v218, 16, v102
	v_and_b32_e32 v219, 0xffff0000, v102
	v_lshlrev_b32_e32 v220, 16, v103
	v_and_b32_e32 v221, 0xffff0000, v103
	v_lshlrev_b32_e32 v18, 16, v108
	v_and_b32_e32 v19, 0xffff0000, v108
	v_lshlrev_b32_e32 v20, 16, v109
	v_and_b32_e32 v21, 0xffff0000, v109
	v_lshlrev_b32_e32 v100, 16, v112
	v_and_b32_e32 v101, 0xffff0000, v112
	v_lshlrev_b32_e32 v102, 16, v113
	v_and_b32_e32 v103, 0xffff0000, v113
	v_mov_b32_e32 v134, v206
	v_pk_mul_f32 v[108:109], v[22:23], v[22:23]
	v_pk_mul_f32 v[112:113], v[136:137], v[136:137]
	v_mov_b32_e32 v139, v126
	v_mov_b32_e32 v203, v170
	v_and_b32_e32 v209, 0xffff0000, v83
	v_mov_b32_e32 v138, v208
	v_mov_b32_e32 v202, v108
	v_mov_b32_e32 v170, v109
	v_pk_fma_f32 v[108:109], v[134:135], v[134:135], v[112:113]
	v_lshlrev_b32_e32 v128, 16, v24
	v_mov_b32_e32 v141, v127
	v_lshlrev_b32_e32 v210, 16, v84
	v_mov_b32_e32 v140, v209
	v_pk_fma_f32 v[108:109], v[138:139], v[138:139], v[108:109]
	v_and_b32_e32 v129, 0xffff0000, v24
	v_mov_b32_e32 v143, v128
	v_and_b32_e32 v211, 0xffff0000, v84
	v_mov_b32_e32 v142, v210
	v_pk_fma_f32 v[108:109], v[140:141], v[140:141], v[108:109]
	v_lshlrev_b32_e32 v130, 16, v25
	v_mov_b32_e32 v145, v129
	v_lshlrev_b32_e32 v212, 16, v85
	v_mov_b32_e32 v144, v211
	v_pk_fma_f32 v[108:109], v[142:143], v[142:143], v[108:109]
	v_and_b32_e32 v131, 0xffff0000, v25
	v_mov_b32_e32 v147, v130
	v_and_b32_e32 v213, 0xffff0000, v85
	v_mov_b32_e32 v146, v212
	v_pk_fma_f32 v[108:109], v[144:145], v[144:145], v[108:109]
	v_mov_b32_e32 v133, v131
	v_mov_b32_e32 v132, v213
	v_pk_fma_f32 v[108:109], v[146:147], v[146:147], v[108:109]
	v_mov_b32_e32 v149, v86
	v_mov_b32_e32 v148, v214
	v_pk_fma_f32 v[108:109], v[132:133], v[132:133], v[108:109]
	v_mov_b32_e32 v151, v87
	v_mov_b32_e32 v150, v215
	v_pk_fma_f32 v[108:109], v[148:149], v[148:149], v[108:109]
	v_mov_b32_e32 v153, v88
	v_mov_b32_e32 v152, v216
	v_pk_fma_f32 v[108:109], v[150:151], v[150:151], v[108:109]
	v_mov_b32_e32 v155, v89
	v_mov_b32_e32 v154, v217
	v_pk_fma_f32 v[108:109], v[152:153], v[152:153], v[108:109]
	v_mov_b32_e32 v157, v90
	v_mov_b32_e32 v156, v218
	v_pk_fma_f32 v[108:109], v[154:155], v[154:155], v[108:109]
	v_mov_b32_e32 v159, v91
	v_mov_b32_e32 v158, v219
	v_pk_fma_f32 v[108:109], v[156:157], v[156:157], v[108:109]
	v_mov_b32_e32 v161, v92
	v_mov_b32_e32 v160, v220
	v_pk_fma_f32 v[108:109], v[158:159], v[158:159], v[108:109]
	v_lshlrev_b32_e32 v66, 16, v14
	v_mov_b32_e32 v163, v93
	v_lshlrev_b32_e32 v194, 16, v78
	v_and_b32_e32 v195, 0xffff0000, v78
	v_lshlrev_b32_e32 v78, 16, v104
	v_mov_b32_e32 v162, v221
	v_pk_fma_f32 v[108:109], v[160:161], v[160:161], v[108:109]
	v_and_b32_e32 v67, 0xffff0000, v14
	v_mov_b32_e32 v165, v66
	v_lshlrev_b32_e32 v196, 16, v79
	v_and_b32_e32 v197, 0xffff0000, v79
	v_and_b32_e32 v79, 0xffff0000, v104
	v_mov_b32_e32 v164, v78
	v_pk_fma_f32 v[108:109], v[162:163], v[162:163], v[108:109]
	v_lshlrev_b32_e32 v68, 16, v15
	v_mov_b32_e32 v167, v67
	v_lshlrev_b32_e32 v198, 16, v80
	v_and_b32_e32 v199, 0xffff0000, v80
	v_lshlrev_b32_e32 v80, 16, v105
	v_mov_b32_e32 v166, v79
	v_pk_fma_f32 v[108:109], v[164:165], v[164:165], v[108:109]
	v_and_b32_e32 v69, 0xffff0000, v15
	v_mov_b32_e32 v169, v68
	v_lshlrev_b32_e32 v200, 16, v81
	v_and_b32_e32 v201, 0xffff0000, v81
	v_and_b32_e32 v81, 0xffff0000, v105
	v_mov_b32_e32 v168, v80
	v_pk_fma_f32 v[108:109], v[166:167], v[166:167], v[108:109]
	v_mov_b32_e32 v175, v69
	v_lshlrev_b32_e32 v82, 16, v106
	v_mov_b32_e32 v174, v81
	v_pk_fma_f32 v[108:109], v[168:169], v[168:169], v[108:109]
	v_mov_b32_e32 v177, v70
	v_and_b32_e32 v83, 0xffff0000, v106
	v_mov_b32_e32 v176, v82
	v_pk_fma_f32 v[108:109], v[174:175], v[174:175], v[108:109]
	v_mov_b32_e32 v179, v71
	v_lshlrev_b32_e32 v84, 16, v107
	v_mov_b32_e32 v178, v83
	v_pk_fma_f32 v[108:109], v[176:177], v[176:177], v[108:109]
	v_mov_b32_e32 v181, v72
	v_and_b32_e32 v85, 0xffff0000, v107
	v_mov_b32_e32 v180, v84
	v_pk_fma_f32 v[108:109], v[178:179], v[178:179], v[108:109]
	v_lshlrev_b32_e32 v14, 16, v10
	v_mov_b32_e32 v183, v73
	v_mov_b32_e32 v182, v85
	v_pk_fma_f32 v[108:109], v[180:181], v[180:181], v[108:109]
	v_and_b32_e32 v15, 0xffff0000, v10
	v_mov_b32_e32 v185, v14
	v_mov_b32_e32 v184, v18
	v_pk_fma_f32 v[108:109], v[182:183], v[182:183], v[108:109]
	v_lshlrev_b32_e32 v10, 16, v11
	v_mov_b32_e32 v187, v15
	v_mov_b32_e32 v186, v19
	v_pk_fma_f32 v[108:109], v[184:185], v[184:185], v[108:109]
	v_and_b32_e32 v11, 0xffff0000, v11
	v_mov_b32_e32 v189, v10
	v_mov_b32_e32 v188, v20
	v_pk_fma_f32 v[108:109], v[186:187], v[186:187], v[108:109]
	v_mov_b32_e32 v193, v11
	v_mov_b32_e32 v192, v21
	v_pk_fma_f32 v[108:109], v[188:189], v[188:189], v[108:109]
	v_lshlrev_b32_e32 v12, 16, v13
	v_and_b32_e32 v13, 0xffff0000, v13
	v_lshlrev_b32_e32 v24, 16, v111
	v_and_b32_e32 v25, 0xffff0000, v111
	v_pk_fma_f32 v[108:109], v[192:193], v[192:193], v[108:109]
	v_pk_mul_f32 v[172:173], v[12:13], v[12:13]
	v_pk_mul_f32 v[110:111], v[24:25], v[24:25]
	v_pk_add_f32 v[108:109], v[202:203], v[108:109]
	v_mov_b32_e32 v205, v172
	v_mov_b32_e32 v204, v110
	v_pk_add_f32 v[108:109], v[170:171], v[108:109]
	v_mov_b32_e32 v172, v111
	v_pk_add_f32 v[108:109], v[204:205], v[108:109]
	v_lshlrev_b32_e32 v104, 16, v114
	v_pk_add_f32 v[108:109], v[172:173], v[108:109]
	ds_bpermute_b32 v111, v1, v109
	ds_bpermute_b32 v110, v1, v108
	v_and_b32_e32 v105, 0xffff0000, v114
	v_lshlrev_b32_e32 v106, 16, v115
	v_and_b32_e32 v107, 0xffff0000, v115
	s_waitcnt lgkmcnt(0)
	v_pk_add_f32 v[108:109], v[108:109], v[110:111]
	ds_bpermute_b32 v111, v61, v109
	ds_bpermute_b32 v110, v61, v108
	s_waitcnt lgkmcnt(0)
	v_pk_add_f32 v[108:109], v[108:109], v[110:111]
	ds_bpermute_b32 v111, v75, v109
	ds_bpermute_b32 v110, v75, v108
	s_waitcnt lgkmcnt(0)
	v_pk_add_f32 v[108:109], v[108:109], v[110:111]
	ds_bpermute_b32 v111, v77, v109
	ds_bpermute_b32 v110, v77, v108
	s_waitcnt lgkmcnt(0)
	v_pk_add_f32 v[108:109], v[108:109], v[110:111]
	ds_bpermute_b32 v111, v94, v109
	ds_bpermute_b32 v110, v94, v108
	s_waitcnt lgkmcnt(0)
	v_pk_add_f32 v[108:109], v[108:109], v[110:111]
	ds_bpermute_b32 v111, v95, v109
	ds_bpermute_b32 v110, v95, v108
	s_waitcnt lgkmcnt(0)
	v_pk_add_f32 v[108:109], v[108:109], v[110:111]
	s_nop 0
	v_pk_fma_f32 v[108:109], v[108:109], s[8:9], v[60:61] op_sel_hi:[1,0,0]
	s_nop 0
	v_mul_f32_e32 v74, 0x4b800000, v109
	v_cmp_gt_f32_e64 s[0:1], s13, v109
	v_mul_f32_e32 v76, 0x4b800000, v108
	v_cmp_gt_f32_e32 vcc, s13, v108
	v_cndmask_b32_e64 v74, v109, v74, s[0:1]
	v_rsq_f32_e32 v74, v74
	v_cndmask_b32_e32 v76, v108, v76, vcc
	v_rsq_f32_e32 v108, v76
	v_mul_f32_e32 v76, 0x45800000, v74
	v_cndmask_b32_e64 v76, v74, v76, s[0:1]
	v_mul_f32_e32 v109, 0x45800000, v108
	v_cndmask_b32_e32 v74, v108, v109, vcc
	v_pk_mul_f32 v[108:109], v[76:77], v[124:125] op_sel_hi:[0,1]
	v_pk_mul_f32 v[110:111], v[76:77], v[126:127] op_sel_hi:[0,1]
	v_pk_mul_f32 v[112:113], v[76:77], v[128:129] op_sel_hi:[0,1]
	v_pk_mul_f32 v[114:115], v[76:77], v[130:131] op_sel_hi:[0,1]
	v_pk_mul_f32 v[124:125], v[74:75], v[206:207] op_sel_hi:[0,1]
	v_pk_mul_f32 v[126:127], v[74:75], v[208:209] op_sel_hi:[0,1]
	v_pk_mul_f32 v[128:129], v[74:75], v[210:211] op_sel_hi:[0,1]
	v_pk_mul_f32 v[130:131], v[74:75], v[212:213] op_sel_hi:[0,1]
	v_pk_mul_f32 v[108:109], v[6:7], v[108:109]
	v_pk_mul_f32 v[110:111], v[8:9], v[110:111]
	v_pk_mul_f32 v[112:113], v[2:3], v[112:113]
	v_pk_mul_f32 v[114:115], v[4:5], v[114:115]
	v_pk_mul_f32 v[124:125], v[6:7], v[124:125]
	v_pk_mul_f32 v[126:127], v[8:9], v[126:127]
	v_pk_mul_f32 v[128:129], v[2:3], v[128:129]
	v_pk_mul_f32 v[130:131], v[4:5], v[130:131]
	v_pk_fma_f32 v[2:3], v[120:121], v[108:109], v[194:195]
	v_pk_fma_f32 v[4:5], v[122:123], v[110:111], v[196:197]
	v_pk_fma_f32 v[6:7], v[116:117], v[112:113], v[198:199]
	v_pk_fma_f32 v[8:9], v[118:119], v[114:115], v[200:201]
	v_pk_fma_f32 v[100:101], v[120:121], v[124:125], v[100:101]
	v_pk_fma_f32 v[102:103], v[122:123], v[126:127], v[102:103]
	v_pk_fma_f32 v[104:105], v[116:117], v[128:129], v[104:105]
	v_pk_fma_f32 v[106:107], v[118:119], v[130:131], v[106:107]
	global_store_dwordx4 v[58:59], v[2:5], off nt
	global_store_dwordx4 v[58:59], v[6:9], off offset:16 nt
	global_store_dwordx4 v[62:63], v[100:103], off offset:-4096 nt
	global_store_dwordx4 v[64:65], v[104:107], off offset:16 nt
	global_load_dwordx4 v[2:5], v[50:51], off offset:2048
	s_nop 0
	global_load_dwordx4 v[6:9], v[50:51], off offset:2064
	global_load_dwordx4 v[100:103], v97, s[10:11]
	global_load_dwordx4 v[104:107], v97, s[10:11] offset:16
	v_pk_mul_f32 v[86:87], v[76:77], v[86:87] op_sel_hi:[0,1]
	v_pk_mul_f32 v[88:89], v[76:77], v[88:89] op_sel_hi:[0,1]
	v_lshlrev_b32_e32 v108, 16, v42
	v_and_b32_e32 v109, 0xffff0000, v42
	v_lshlrev_b32_e32 v42, 16, v43
	v_and_b32_e32 v43, 0xffff0000, v43
	v_pk_mul_f32 v[90:91], v[76:77], v[90:91] op_sel_hi:[0,1]
	v_pk_mul_f32 v[92:93], v[76:77], v[92:93] op_sel_hi:[0,1]
	v_pk_mul_f32 v[116:117], v[74:75], v[214:215] op_sel_hi:[0,1]
	v_pk_mul_f32 v[118:119], v[74:75], v[216:217] op_sel_hi:[0,1]
	v_pk_mul_f32 v[120:121], v[74:75], v[218:219] op_sel_hi:[0,1]
	v_pk_mul_f32 v[122:123], v[74:75], v[220:221] op_sel_hi:[0,1]
	v_lshlrev_b32_e32 v110, 16, v44
	v_and_b32_e32 v111, 0xffff0000, v44
	v_lshlrev_b32_e32 v44, 16, v45
	v_and_b32_e32 v45, 0xffff0000, v45
	v_lshlrev_b32_e32 v112, 16, v46
	v_and_b32_e32 v113, 0xffff0000, v46
	v_lshlrev_b32_e32 v46, 16, v47
	v_and_b32_e32 v47, 0xffff0000, v47
	v_lshlrev_b32_e32 v114, 16, v48
	v_and_b32_e32 v115, 0xffff0000, v48
	v_lshlrev_b32_e32 v48, 16, v49
	v_and_b32_e32 v49, 0xffff0000, v49
	v_pk_mul_f32 v[66:67], v[76:77], v[66:67] op_sel_hi:[0,1]
	v_pk_mul_f32 v[68:69], v[76:77], v[68:69] op_sel_hi:[0,1]
	v_pk_mul_f32 v[70:71], v[76:77], v[70:71] op_sel_hi:[0,1]
	v_pk_mul_f32 v[72:73], v[76:77], v[72:73] op_sel_hi:[0,1]
	v_pk_mul_f32 v[78:79], v[74:75], v[78:79] op_sel_hi:[0,1]
	v_pk_mul_f32 v[80:81], v[74:75], v[80:81] op_sel_hi:[0,1]
	v_pk_mul_f32 v[82:83], v[74:75], v[82:83] op_sel_hi:[0,1]
	v_pk_mul_f32 v[84:85], v[74:75], v[84:85] op_sel_hi:[0,1]
	v_pk_mul_f32 v[14:15], v[76:77], v[14:15] op_sel_hi:[0,1]
	v_pk_mul_f32 v[10:11], v[76:77], v[10:11] op_sel_hi:[0,1]
	v_pk_mul_f32 v[16:17], v[76:77], v[16:17] op_sel_hi:[0,1]
	v_pk_mul_f32 v[12:13], v[76:77], v[12:13] op_sel_hi:[0,1]
	v_pk_mul_f32 v[18:19], v[74:75], v[18:19] op_sel_hi:[0,1]
	v_pk_mul_f32 v[20:21], v[74:75], v[20:21] op_sel_hi:[0,1]
	v_pk_mul_f32 v[22:23], v[74:75], v[22:23] op_sel_hi:[0,1]
	v_pk_mul_f32 v[24:25], v[74:75], v[24:25] op_sel_hi:[0,1]
	s_waitcnt vmcnt(3)
	v_pk_mul_f32 v[86:87], v[2:3], v[86:87]
	v_pk_mul_f32 v[88:89], v[4:5], v[88:89]
	s_waitcnt vmcnt(2)
	v_pk_mul_f32 v[90:91], v[6:7], v[90:91]
	v_pk_mul_f32 v[92:93], v[8:9], v[92:93]
	v_pk_mul_f32 v[116:117], v[2:3], v[116:117]
	v_pk_mul_f32 v[118:119], v[4:5], v[118:119]
	v_pk_mul_f32 v[120:121], v[6:7], v[120:121]
	v_pk_mul_f32 v[122:123], v[8:9], v[122:123]
	s_waitcnt vmcnt(1)
	v_pk_fma_f32 v[2:3], v[100:101], v[86:87], v[108:109]
	v_pk_fma_f32 v[4:5], v[102:103], v[88:89], v[42:43]
	s_waitcnt vmcnt(0)
	v_pk_fma_f32 v[6:7], v[104:105], v[90:91], v[110:111]
	v_pk_fma_f32 v[8:9], v[106:107], v[92:93], v[44:45]
	v_pk_fma_f32 v[42:43], v[100:101], v[116:117], v[112:113]
	v_pk_fma_f32 v[44:45], v[102:103], v[118:119], v[46:47]
	v_pk_fma_f32 v[46:47], v[104:105], v[120:121], v[114:115]
	v_pk_fma_f32 v[48:49], v[106:107], v[122:123], v[48:49]
	global_store_dwordx4 v[58:59], v[2:5], off offset:2048 nt
	global_store_dwordx4 v[58:59], v[6:9], off offset:2064 nt
	global_store_dwordx4 v[64:65], v[42:45], off offset:2048 nt
	global_store_dwordx4 v[64:65], v[46:49], off offset:2064 nt
	global_load_dwordx4 v[2:5], v[52:53], off
	s_nop 0
	global_load_dwordx4 v[6:9], v[52:53], off offset:16
	global_load_dwordx4 v[42:45], v98, s[10:11]
	global_load_dwordx4 v[46:49], v98, s[10:11] offset:16
	v_add_co_u32_e32 v64, vcc, s3, v58
	v_lshlrev_b32_e32 v86, 16, v34
	v_and_b32_e32 v87, 0xffff0000, v34
	v_lshlrev_b32_e32 v34, 16, v35
	v_and_b32_e32 v35, 0xffff0000, v35
	v_addc_co_u32_e32 v65, vcc, 0, v59, vcc
	v_lshlrev_b32_e32 v88, 16, v36
	v_and_b32_e32 v89, 0xffff0000, v36
	v_lshlrev_b32_e32 v36, 16, v37
	v_and_b32_e32 v37, 0xffff0000, v37
	v_lshlrev_b32_e32 v90, 16, v38
	v_and_b32_e32 v91, 0xffff0000, v38
	v_lshlrev_b32_e32 v38, 16, v39
	v_and_b32_e32 v39, 0xffff0000, v39
	v_lshlrev_b32_e32 v92, 16, v40
	v_and_b32_e32 v93, 0xffff0000, v40
	v_lshlrev_b32_e32 v40, 16, v41
	v_and_b32_e32 v41, 0xffff0000, v41
	v_lshl_add_u64 v[58:59], v[58:59], 0, s[6:7]
	s_waitcnt vmcnt(3)
	v_pk_mul_f32 v[66:67], v[2:3], v[66:67]
	v_pk_mul_f32 v[68:69], v[4:5], v[68:69]
	s_waitcnt vmcnt(2)
	v_pk_mul_f32 v[70:71], v[6:7], v[70:71]
	v_pk_mul_f32 v[72:73], v[8:9], v[72:73]
	v_pk_mul_f32 v[78:79], v[2:3], v[78:79]
	v_pk_mul_f32 v[80:81], v[4:5], v[80:81]
	v_pk_mul_f32 v[82:83], v[6:7], v[82:83]
	v_pk_mul_f32 v[84:85], v[8:9], v[84:85]
	s_waitcnt vmcnt(1)
	v_pk_fma_f32 v[2:3], v[42:43], v[66:67], v[86:87]
	v_pk_fma_f32 v[4:5], v[44:45], v[68:69], v[34:35]
	s_waitcnt vmcnt(0)
	v_pk_fma_f32 v[6:7], v[46:47], v[70:71], v[88:89]
	v_pk_fma_f32 v[8:9], v[48:49], v[72:73], v[36:37]
	v_pk_fma_f32 v[34:35], v[42:43], v[78:79], v[90:91]
	v_pk_fma_f32 v[36:37], v[44:45], v[80:81], v[38:39]
	v_pk_fma_f32 v[38:39], v[46:47], v[82:83], v[92:93]
	v_pk_fma_f32 v[40:41], v[48:49], v[84:85], v[40:41]
	global_store_dwordx4 v[64:65], v[2:5], off nt
	global_store_dwordx4 v[64:65], v[6:9], off offset:16 nt
	global_store_dwordx4 v[62:63], v[34:37], off nt
	global_store_dwordx4 v[62:63], v[38:41], off offset:16 nt
	global_load_dwordx4 v[2:5], v[54:55], off
	s_nop 0
	global_load_dwordx4 v[6:9], v[54:55], off offset:16
	global_load_dwordx4 v[34:37], v99, s[10:11]
	global_load_dwordx4 v[38:41], v99, s[10:11] offset:16
	v_lshlrev_b32_e32 v42, 16, v26
	v_and_b32_e32 v43, 0xffff0000, v26
	v_lshlrev_b32_e32 v26, 16, v27
	v_and_b32_e32 v27, 0xffff0000, v27
	v_lshlrev_b32_e32 v44, 16, v28
	v_and_b32_e32 v45, 0xffff0000, v28
	v_lshlrev_b32_e32 v28, 16, v29
	v_and_b32_e32 v29, 0xffff0000, v29
	v_lshlrev_b32_e32 v46, 16, v30
	v_and_b32_e32 v47, 0xffff0000, v30
	v_lshlrev_b32_e32 v30, 16, v31
	v_and_b32_e32 v31, 0xffff0000, v31
	v_lshlrev_b32_e32 v48, 16, v32
	v_and_b32_e32 v49, 0xffff0000, v32
	v_lshlrev_b32_e32 v32, 16, v33
	v_and_b32_e32 v33, 0xffff0000, v33
	s_waitcnt vmcnt(3)
	v_pk_mul_f32 v[14:15], v[14:15], v[2:3]
	v_pk_mul_f32 v[10:11], v[10:11], v[4:5]
	s_waitcnt vmcnt(2)
	v_pk_mul_f32 v[16:17], v[16:17], v[6:7]
	v_pk_mul_f32 v[12:13], v[12:13], v[8:9]
	v_pk_mul_f32 v[18:19], v[2:3], v[18:19]
	v_pk_mul_f32 v[20:21], v[4:5], v[20:21]
	v_pk_mul_f32 v[22:23], v[6:7], v[22:23]
	v_pk_mul_f32 v[24:25], v[8:9], v[24:25]
	s_waitcnt vmcnt(1)
	v_pk_fma_f32 v[2:3], v[14:15], v[34:35], v[42:43]
	v_pk_fma_f32 v[4:5], v[10:11], v[36:37], v[26:27]
	s_waitcnt vmcnt(0)
	v_pk_fma_f32 v[6:7], v[16:17], v[38:39], v[44:45]
	v_pk_fma_f32 v[8:9], v[12:13], v[40:41], v[28:29]
	v_pk_fma_f32 v[10:11], v[34:35], v[18:19], v[46:47]
	v_pk_fma_f32 v[12:13], v[36:37], v[20:21], v[30:31]
	v_pk_fma_f32 v[14:15], v[38:39], v[22:23], v[48:49]
	v_pk_fma_f32 v[16:17], v[40:41], v[24:25], v[32:33]
	global_store_dwordx4 v[64:65], v[2:5], off offset:2048 nt
	global_store_dwordx4 v[64:65], v[6:9], off offset:2064 nt
	global_store_dwordx4 v[62:63], v[10:13], off offset:2048 nt
	global_store_dwordx4 v[62:63], v[14:17], off offset:2064 nt
	v_mov_b32_e32 v1, v222
	v_mov_b32_e32 v138, v223
	v_mov_b32_e32 v139, v224
	v_mov_b32_e32 v140, v225
	v_mov_b32_e32 v141, v226
	v_mov_b32_e32 v142, v227
	v_mov_b32_e32 v143, v228
	v_mov_b32_e32 v144, v229
	v_mov_b32_e32 v145, v230
	v_mov_b32_e32 v154, v231
	v_mov_b32_e32 v155, v232
	v_mov_b32_e32 v156, v233
	v_mov_b32_e32 v157, v234
	v_mov_b32_e32 v158, v235
	v_mov_b32_e32 v159, v236
	v_mov_b32_e32 v160, v237
	v_readlane_b32 s0, v255, 40
	v_readlane_b32 s1, v255, 41
	v_readlane_b32 s2, v255, 42
	v_readlane_b32 s3, v255, 43
	v_readlane_b32 s6, v255, 44
	v_readlane_b32 s7, v255, 45
	v_readlane_b32 s25, v255, 46
	v_readlane_b32 s26, v255, 47
	v_readlane_b32 s27, v255, 48
	v_readlane_b32 s28, v255, 49
	v_readlane_b32 s49, v255, 50
	s_waitcnt lgkmcnt(0)
	s_mov_b64 s[8:9], exec
	v_readlane_b32 s10, v254, 2
	v_readlane_b32 s11, v254, 3
	s_nop 1
	s_and_b64 s[10:11], s[8:9], s[10:11]
	s_mov_b64 exec, s[10:11]
	s_cbranch_execz .Llb865_join
	v_mov_b32_e32 v4, 0x23fc4
	ds_read_b32 v3, v4
	s_add_u32 s12, s62, 0x40d000
	s_addc_u32 s13, s63, 0
	v_mov_b32_e32 v4, 0x400
	s_mov_b32 s16, 0
	buffer_inv sc1
